# in_proj: per-tile vmcnt(0) drain in front of the K-loop removed (counted waits already cover it)
# baseline (speedup 1.0000x reference)
.LBB0_927:
	s_ashr_i32 s7, s6, 31
	s_lshl_b64 s[10:11], s[6:7], 19
	s_add_u32 s10, s20, s10
	s_addc_u32 s11, s21, s11
	s_and_b64 s[14:15], s[38:39], exec
	s_cselect_b32 s7, s11, s23
	s_cselect_b32 s13, s10, s22
	s_ashr_i32 s5, s4, 31
	s_lshl_b64 s[14:15], s[4:5], 19
	s_add_u32 s14, s26, s14
	s_addc_u32 s15, s27, s15
	s_and_b64 s[18:19], s[38:39], exec
	s_cselect_b32 s5, s15, s43
	s_cselect_b32 s17, s14, s42
	s_add_u32 s40, s22, 0x40080
	s_addc_u32 s41, s23, 0
	s_add_u32 s42, s42, 0x100
	v_mov_b32_e32 v4, 0
	s_addc_u32 s43, s43, 0
	s_mov_b32 s51, -2
	v_mov_b32_e32 v5, v4
	v_mov_b32_e32 v6, v4
	v_mov_b32_e32 v7, v4
	v_mov_b32_e32 v8, v4
	v_mov_b32_e32 v9, v4
	v_mov_b32_e32 v10, v4
	v_mov_b32_e32 v11, v4
	v_mov_b32_e32 v16, v4
	v_mov_b32_e32 v17, v4
	v_mov_b32_e32 v18, v4
	v_mov_b32_e32 v19, v4
	v_mov_b32_e32 v24, v4
	v_mov_b32_e32 v25, v4
	v_mov_b32_e32 v26, v4
	v_mov_b32_e32 v27, v4
	v_mov_b32_e32 v32, v4
	v_mov_b32_e32 v33, v4
	v_mov_b32_e32 v34, v4
	v_mov_b32_e32 v35, v4
	v_mov_b32_e32 v40, v4
	v_mov_b32_e32 v41, v4
	v_mov_b32_e32 v42, v4
	v_mov_b32_e32 v43, v4
	v_mov_b32_e32 v48, v4
	v_mov_b32_e32 v49, v4
	v_mov_b32_e32 v50, v4
	v_mov_b32_e32 v51, v4
	v_mov_b32_e32 v56, v4
	v_mov_b32_e32 v57, v4
	v_mov_b32_e32 v58, v4
	v_mov_b32_e32 v59, v4
	v_mov_b32_e32 v12, v4
	v_mov_b32_e32 v13, v4
	v_mov_b32_e32 v14, v4
	v_mov_b32_e32 v15, v4
	v_mov_b32_e32 v20, v4
	v_mov_b32_e32 v21, v4
	v_mov_b32_e32 v22, v4
	v_mov_b32_e32 v23, v4
	v_mov_b32_e32 v28, v4
	v_mov_b32_e32 v29, v4
	v_mov_b32_e32 v30, v4
	v_mov_b32_e32 v31, v4
	v_mov_b32_e32 v36, v4
	v_mov_b32_e32 v37, v4
	v_mov_b32_e32 v38, v4
	v_mov_b32_e32 v39, v4
	v_mov_b32_e32 v44, v4
	v_mov_b32_e32 v45, v4
	v_mov_b32_e32 v46, v4
	v_mov_b32_e32 v47, v4
	v_mov_b32_e32 v52, v4
	v_mov_b32_e32 v53, v4
	v_mov_b32_e32 v54, v4
	v_mov_b32_e32 v55, v4
	v_mov_b32_e32 v60, v4
	v_mov_b32_e32 v61, v4
	v_mov_b32_e32 v62, v4
	v_mov_b32_e32 v63, v4
	v_mov_b32_e32 v64, v4
	v_mov_b32_e32 v65, v4
	v_mov_b32_e32 v66, v4
	v_mov_b32_e32 v67, v4
	v_mov_b32_e32 v68, v4
	v_mov_b32_e32 v69, v4
	v_mov_b32_e32 v70, v4
	v_mov_b32_e32 v71, v4
	v_mov_b32_e32 v72, v4
	v_mov_b32_e32 v73, v4
	v_mov_b32_e32 v74, v4
	v_mov_b32_e32 v75, v4
	v_mov_b32_e32 v80, v4
	v_mov_b32_e32 v81, v4
	v_mov_b32_e32 v82, v4
	v_mov_b32_e32 v83, v4
	v_mov_b32_e32 v88, v4
	v_mov_b32_e32 v89, v4
	v_mov_b32_e32 v90, v4
	v_mov_b32_e32 v91, v4
	v_mov_b32_e32 v96, v4
	v_mov_b32_e32 v97, v4
	v_mov_b32_e32 v98, v4
	v_mov_b32_e32 v99, v4
	v_mov_b32_e32 v104, v4
	v_mov_b32_e32 v105, v4
	v_mov_b32_e32 v106, v4
	v_mov_b32_e32 v107, v4
	v_mov_b32_e32 v112, v4
	v_mov_b32_e32 v113, v4
	v_mov_b32_e32 v114, v4
	v_mov_b32_e32 v115, v4
	v_mov_b32_e32 v120, v4
	v_mov_b32_e32 v121, v4
	v_mov_b32_e32 v122, v4
	v_mov_b32_e32 v123, v4
	v_mov_b32_e32 v76, v4
	v_mov_b32_e32 v77, v4
	v_mov_b32_e32 v78, v4
	v_mov_b32_e32 v79, v4
	v_mov_b32_e32 v84, v4
	v_mov_b32_e32 v85, v4
	v_mov_b32_e32 v86, v4
	v_mov_b32_e32 v87, v4
	v_mov_b32_e32 v92, v4
	v_mov_b32_e32 v93, v4
	v_mov_b32_e32 v94, v4
	v_mov_b32_e32 v95, v4
	v_mov_b32_e32 v100, v4
	v_mov_b32_e32 v101, v4
	v_mov_b32_e32 v102, v4
	v_mov_b32_e32 v103, v4
	v_mov_b32_e32 v108, v4
	v_mov_b32_e32 v109, v4
	v_mov_b32_e32 v110, v4
	v_mov_b32_e32 v111, v4
	v_mov_b32_e32 v116, v4
	v_mov_b32_e32 v117, v4
	v_mov_b32_e32 v118, v4
	v_mov_b32_e32 v119, v4
	v_mov_b32_e32 v124, v4
	v_mov_b32_e32 v125, v4
	v_mov_b32_e32 v126, v4
	v_mov_b32_e32 v127, v4
	v_mov_b32_e32 v128, v4
	v_mov_b32_e32 v129, v4
	v_mov_b32_e32 v130, v4
	v_mov_b32_e32 v131, v4
.LBB0_928:
	s_add_u32 s18, s40, 0xfffc0080
	s_addc_u32 s19, s41, -1
	s_add_i32 s52, 0, 0x10000
	s_cmp_eq_u32 s51, 12
	s_cselect_b32 s25, s7, s19
	s_cselect_b32 s24, s13, s18
	s_cselect_b32 s23, s5, s43
	s_cselect_b32 s22, s17, s42
	s_add_i32 s53, 0, 0x14000
	v_add_u32_e32 v166, s52, v152
	v_add_u32_e32 v182, s53, v152
	ds_read_b128 v[148:151], v166
	ds_read_b128 v[158:161], v166 offset:1024
	ds_read_b128 v[162:165], v166 offset:2048
	ds_read_b128 v[166:169], v166 offset:3072
	ds_read_b128 v[170:173], v182
	ds_read_b128 v[174:177], v182 offset:1024
	ds_read_b128 v[178:181], v182 offset:2048
	ds_read_b128 v[182:185], v182 offset:3072
	s_add_i32 m0, s29, 0xc000
	ds_read_b128 v[186:189], v157
	ds_read_b128 v[208:211], v157 offset:1024
	ds_read_b128 v[212:215], v157 offset:2048
	ds_read_b128 v[216:219], v157 offset:3072
	ds_read_b128 v[220:223], v157 offset:4096
	ds_read_b128 v[224:227], v157 offset:5120
	ds_read_b128 v[228:231], v157 offset:6144
	ds_read_b128 v[232:235], v157 offset:7168
	global_load_lds_dwordx4 v144, s[40:41]
	s_add_i32 m0, s29, 0xe000
	s_nop 0
	global_load_lds_dwordx4 v146, s[40:41]
	s_waitcnt vmcnt(8)
	s_waitcnt lgkmcnt(0)
	s_barrier
	s_setprio 1
	s_waitcnt lgkmcnt(0)
	v_mfma_f32_16x16x32_bf16 v[128:131], v[148:151], v[186:189], v[128:131]
	v_mfma_f32_16x16x32_bf16 v[124:127], v[162:165], v[186:189], v[124:127]
	v_mfma_f32_16x16x32_bf16 v[116:119], v[148:151], v[212:215], v[116:119]
	v_mfma_f32_16x16x32_bf16 v[108:111], v[162:165], v[212:215], v[108:111]
	v_mfma_f32_16x16x32_bf16 v[100:103], v[148:151], v[220:223], v[100:103]
	v_mfma_f32_16x16x32_bf16 v[92:95], v[162:165], v[220:223], v[92:95]
	v_mfma_f32_16x16x32_bf16 v[84:87], v[148:151], v[228:231], v[84:87]
	v_mfma_f32_16x16x32_bf16 v[76:79], v[162:165], v[228:231], v[76:79]
	v_mfma_f32_16x16x32_bf16 v[128:131], v[158:161], v[208:211], v[128:131]
	v_mfma_f32_16x16x32_bf16 v[124:127], v[166:169], v[208:211], v[124:127]
	v_mfma_f32_16x16x32_bf16 v[116:119], v[158:161], v[216:219], v[116:119]
	v_mfma_f32_16x16x32_bf16 v[108:111], v[166:169], v[216:219], v[108:111]
	v_mfma_f32_16x16x32_bf16 v[100:103], v[158:161], v[224:227], v[100:103]
	v_mfma_f32_16x16x32_bf16 v[92:95], v[166:169], v[224:227], v[92:95]
	v_mfma_f32_16x16x32_bf16 v[84:87], v[158:161], v[232:235], v[84:87]
	v_mfma_f32_16x16x32_bf16 v[76:79], v[166:169], v[232:235], v[76:79]
	s_setprio 0
	s_setprio 1
	v_mfma_f32_16x16x32_bf16 v[120:123], v[170:173], v[186:189], v[120:123]
	v_mfma_f32_16x16x32_bf16 v[112:115], v[178:181], v[186:189], v[112:115]
	v_mfma_f32_16x16x32_bf16 v[104:107], v[170:173], v[212:215], v[104:107]
	v_mfma_f32_16x16x32_bf16 v[96:99], v[178:181], v[212:215], v[96:99]
	v_mfma_f32_16x16x32_bf16 v[88:91], v[170:173], v[220:223], v[88:91]
	v_mfma_f32_16x16x32_bf16 v[80:83], v[178:181], v[220:223], v[80:83]
	v_mfma_f32_16x16x32_bf16 v[72:75], v[170:173], v[228:231], v[72:75]
	v_mfma_f32_16x16x32_bf16 v[68:71], v[178:181], v[228:231], v[68:71]
	v_mfma_f32_16x16x32_bf16 v[120:123], v[174:177], v[208:211], v[120:123]
	v_mfma_f32_16x16x32_bf16 v[112:115], v[182:185], v[208:211], v[112:115]
	v_mfma_f32_16x16x32_bf16 v[104:107], v[174:177], v[216:219], v[104:107]
	v_mfma_f32_16x16x32_bf16 v[96:99], v[182:185], v[216:219], v[96:99]
	v_mfma_f32_16x16x32_bf16 v[88:91], v[174:177], v[224:227], v[88:91]
	v_mfma_f32_16x16x32_bf16 v[80:83], v[182:185], v[224:227], v[80:83]
	v_mfma_f32_16x16x32_bf16 v[72:75], v[174:177], v[232:235], v[72:75]
	v_mfma_f32_16x16x32_bf16 v[68:71], v[182:185], v[232:235], v[68:71]
	s_setprio 0
	s_barrier
	s_add_i32 s18, s52, s28
	s_mov_b32 m0, s18
	ds_read_b128 v[186:189], v157 offset:16384
	ds_read_b128 v[208:211], v157 offset:17408
	ds_read_b128 v[212:215], v157 offset:18432
	ds_read_b128 v[216:219], v157 offset:19456
	ds_read_b128 v[220:223], v157 offset:20480
	ds_read_b128 v[224:227], v157 offset:21504
	ds_read_b128 v[228:231], v157 offset:22528
	ds_read_b128 v[232:235], v157 offset:23552
	global_load_lds_dwordx4 v2, s[22:23]
	s_add_i32 m0, s18, 0x2000
	s_add_u32 s18, s22, 0x10000
	s_addc_u32 s19, s23, 0
	s_add_i32 s52, s53, s28
	global_load_lds_dwordx4 v142, s[22:23]
	s_mov_b32 m0, s52
	s_nop 0
	global_load_lds_dwordx4 v2, s[18:19]
	s_add_i32 m0, s52, 0x2000
	s_nop 0
	global_load_lds_dwordx4 v142, s[18:19]
	s_mov_b32 m0, s29
	s_nop 0
	global_load_lds_dwordx4 v0, s[24:25]
	s_mov_b32 m0, s44
	s_nop 0
	global_load_lds_dwordx4 v140, s[24:25]
	s_waitcnt vmcnt(8)
	s_waitcnt lgkmcnt(0)
	s_barrier
	s_setprio 1
	s_waitcnt lgkmcnt(0)
	v_mfma_f32_16x16x32_bf16 v[64:67], v[148:151], v[186:189], v[64:67]
	v_mfma_f32_16x16x32_bf16 v[60:63], v[162:165], v[186:189], v[60:63]
	v_mfma_f32_16x16x32_bf16 v[52:55], v[148:151], v[212:215], v[52:55]
	v_mfma_f32_16x16x32_bf16 v[44:47], v[162:165], v[212:215], v[44:47]
	v_mfma_f32_16x16x32_bf16 v[36:39], v[148:151], v[220:223], v[36:39]
	v_mfma_f32_16x16x32_bf16 v[28:31], v[162:165], v[220:223], v[28:31]
	v_mfma_f32_16x16x32_bf16 v[20:23], v[148:151], v[228:231], v[20:23]
	v_mfma_f32_16x16x32_bf16 v[12:15], v[162:165], v[228:231], v[12:15]
	v_mfma_f32_16x16x32_bf16 v[64:67], v[158:161], v[208:211], v[64:67]
	v_mfma_f32_16x16x32_bf16 v[60:63], v[166:169], v[208:211], v[60:63]
	v_mfma_f32_16x16x32_bf16 v[52:55], v[158:161], v[216:219], v[52:55]
	v_mfma_f32_16x16x32_bf16 v[44:47], v[166:169], v[216:219], v[44:47]
	v_mfma_f32_16x16x32_bf16 v[36:39], v[158:161], v[224:227], v[36:39]
	v_mfma_f32_16x16x32_bf16 v[28:31], v[166:169], v[224:227], v[28:31]
	v_mfma_f32_16x16x32_bf16 v[20:23], v[158:161], v[232:235], v[20:23]
	v_mfma_f32_16x16x32_bf16 v[12:15], v[166:169], v[232:235], v[12:15]
	s_setprio 0
	s_setprio 1
	v_mfma_f32_16x16x32_bf16 v[56:59], v[170:173], v[186:189], v[56:59]
	v_mfma_f32_16x16x32_bf16 v[48:51], v[178:181], v[186:189], v[48:51]
	v_mfma_f32_16x16x32_bf16 v[40:43], v[170:173], v[212:215], v[40:43]
	v_mfma_f32_16x16x32_bf16 v[32:35], v[178:181], v[212:215], v[32:35]
	v_mfma_f32_16x16x32_bf16 v[24:27], v[170:173], v[220:223], v[24:27]
	v_mfma_f32_16x16x32_bf16 v[16:19], v[178:181], v[220:223], v[16:19]
	v_mfma_f32_16x16x32_bf16 v[8:11], v[170:173], v[228:231], v[8:11]
	v_mfma_f32_16x16x32_bf16 v[4:7], v[178:181], v[228:231], v[4:7]
	v_mfma_f32_16x16x32_bf16 v[56:59], v[174:177], v[208:211], v[56:59]
	v_mfma_f32_16x16x32_bf16 v[48:51], v[182:185], v[208:211], v[48:51]
	v_mfma_f32_16x16x32_bf16 v[40:43], v[174:177], v[216:219], v[40:43]
	v_mfma_f32_16x16x32_bf16 v[32:35], v[182:185], v[216:219], v[32:35]
	v_mfma_f32_16x16x32_bf16 v[24:27], v[174:177], v[224:227], v[24:27]
	v_mfma_f32_16x16x32_bf16 v[16:19], v[182:185], v[224:227], v[16:19]
	v_mfma_f32_16x16x32_bf16 v[8:11], v[174:177], v[232:235], v[8:11]
	v_mfma_f32_16x16x32_bf16 v[4:7], v[182:185], v[232:235], v[4:7]
	s_setprio 0
	s_barrier
	s_add_i32 s52, 0, 0x18000
	s_add_i32 s53, 0, 0x1c000
	v_add_u32_e32 v166, s52, v152
	v_add_u32_e32 v182, s53, v152
	ds_read_b128 v[148:151], v166
	ds_read_b128 v[158:161], v166 offset:1024
	ds_read_b128 v[162:165], v166 offset:2048
	ds_read_b128 v[166:169], v166 offset:3072
	ds_read_b128 v[170:173], v182
	ds_read_b128 v[174:177], v182 offset:1024
	ds_read_b128 v[178:181], v182 offset:2048
	ds_read_b128 v[182:185], v182 offset:3072
	s_add_u32 s18, s24, 0x40000
	s_addc_u32 s19, s25, 0
	s_mov_b32 m0, s45
	ds_read_b128 v[186:189], v157 offset:32768
	ds_read_b128 v[208:211], v157 offset:33792
	ds_read_b128 v[212:215], v157 offset:34816
	ds_read_b128 v[216:219], v157 offset:35840
	ds_read_b128 v[220:223], v157 offset:36864
	ds_read_b128 v[224:227], v157 offset:37888
	ds_read_b128 v[228:231], v157 offset:38912
	ds_read_b128 v[232:235], v157 offset:39936
	global_load_lds_dwordx4 v0, s[18:19]
	s_mov_b32 m0, s46
	s_nop 0
	global_load_lds_dwordx4 v140, s[18:19]
	s_waitcnt vmcnt(8)
	s_waitcnt lgkmcnt(0)
	s_barrier
	s_setprio 1
	s_waitcnt lgkmcnt(0)
	v_mfma_f32_16x16x32_bf16 v[128:131], v[148:151], v[186:189], v[128:131]
	v_mfma_f32_16x16x32_bf16 v[124:127], v[162:165], v[186:189], v[124:127]
	v_mfma_f32_16x16x32_bf16 v[116:119], v[148:151], v[212:215], v[116:119]
	v_mfma_f32_16x16x32_bf16 v[108:111], v[162:165], v[212:215], v[108:111]
	v_mfma_f32_16x16x32_bf16 v[100:103], v[148:151], v[220:223], v[100:103]
	v_mfma_f32_16x16x32_bf16 v[92:95], v[162:165], v[220:223], v[92:95]
	v_mfma_f32_16x16x32_bf16 v[84:87], v[148:151], v[228:231], v[84:87]
	v_mfma_f32_16x16x32_bf16 v[76:79], v[162:165], v[228:231], v[76:79]
	v_mfma_f32_16x16x32_bf16 v[128:131], v[158:161], v[208:211], v[128:131]
	v_mfma_f32_16x16x32_bf16 v[124:127], v[166:169], v[208:211], v[124:127]
	v_mfma_f32_16x16x32_bf16 v[116:119], v[158:161], v[216:219], v[116:119]
	v_mfma_f32_16x16x32_bf16 v[108:111], v[166:169], v[216:219], v[108:111]
	v_mfma_f32_16x16x32_bf16 v[100:103], v[158:161], v[224:227], v[100:103]
	v_mfma_f32_16x16x32_bf16 v[92:95], v[166:169], v[224:227], v[92:95]
	v_mfma_f32_16x16x32_bf16 v[84:87], v[158:161], v[232:235], v[84:87]
	v_mfma_f32_16x16x32_bf16 v[76:79], v[166:169], v[232:235], v[76:79]
	s_setprio 0
	s_setprio 1
	v_mfma_f32_16x16x32_bf16 v[120:123], v[170:173], v[186:189], v[120:123]
	v_mfma_f32_16x16x32_bf16 v[112:115], v[178:181], v[186:189], v[112:115]
	v_mfma_f32_16x16x32_bf16 v[104:107], v[170:173], v[212:215], v[104:107]
	v_mfma_f32_16x16x32_bf16 v[96:99], v[178:181], v[212:215], v[96:99]
	v_mfma_f32_16x16x32_bf16 v[88:91], v[170:173], v[220:223], v[88:91]
	v_mfma_f32_16x16x32_bf16 v[80:83], v[178:181], v[220:223], v[80:83]
	v_mfma_f32_16x16x32_bf16 v[72:75], v[170:173], v[228:231], v[72:75]
	v_mfma_f32_16x16x32_bf16 v[68:71], v[178:181], v[228:231], v[68:71]
	v_mfma_f32_16x16x32_bf16 v[120:123], v[174:177], v[208:211], v[120:123]
	v_mfma_f32_16x16x32_bf16 v[112:115], v[182:185], v[208:211], v[112:115]
	v_mfma_f32_16x16x32_bf16 v[104:107], v[174:177], v[216:219], v[104:107]
	v_mfma_f32_16x16x32_bf16 v[96:99], v[182:185], v[216:219], v[96:99]
	v_mfma_f32_16x16x32_bf16 v[88:91], v[174:177], v[224:227], v[88:91]
	v_mfma_f32_16x16x32_bf16 v[80:83], v[182:185], v[224:227], v[80:83]
	v_mfma_f32_16x16x32_bf16 v[72:75], v[174:177], v[232:235], v[72:75]
	v_mfma_f32_16x16x32_bf16 v[68:71], v[182:185], v[232:235], v[68:71]
	s_setprio 0
	s_barrier
	s_add_i32 s18, s52, s28
	s_add_u32 s100, s22, 0x80
	s_addc_u32 s101, s23, 0
	s_mov_b32 m0, s18
	ds_read_b128 v[186:189], v157 offset:49152
	ds_read_b128 v[208:211], v157 offset:50176
	ds_read_b128 v[212:215], v157 offset:51200
	ds_read_b128 v[216:219], v157 offset:52224
	ds_read_b128 v[220:223], v157 offset:53248
	ds_read_b128 v[224:227], v157 offset:54272
	ds_read_b128 v[228:231], v157 offset:55296
	ds_read_b128 v[232:235], v157 offset:56320
	global_load_lds_dwordx4 v2, s[100:101]
	s_add_i32 m0, s18, 0x2000
	s_add_u32 s18, s22, 0x10080
	s_addc_u32 s19, s23, 0
	s_add_i32 s22, s53, s28
	global_load_lds_dwordx4 v142, s[100:101]
	s_mov_b32 m0, s22
	s_nop 0
	global_load_lds_dwordx4 v2, s[18:19]
	s_add_i32 m0, s22, 0x2000
	s_nop 0
	global_load_lds_dwordx4 v142, s[18:19]
	s_add_u32 s100, s24, 0x80
	s_addc_u32 s101, s25, 0
	s_mov_b32 m0, s47
	s_nop 0
	global_load_lds_dwordx4 v0, s[100:101]
	s_mov_b32 m0, s48
	s_nop 0
	global_load_lds_dwordx4 v140, s[100:101]
	s_waitcnt vmcnt(8)
	s_waitcnt lgkmcnt(0)
	s_barrier
	s_setprio 1
	s_waitcnt lgkmcnt(0)
	v_mfma_f32_16x16x32_bf16 v[64:67], v[148:151], v[186:189], v[64:67]
	v_mfma_f32_16x16x32_bf16 v[60:63], v[162:165], v[186:189], v[60:63]
	v_mfma_f32_16x16x32_bf16 v[52:55], v[148:151], v[212:215], v[52:55]
	v_mfma_f32_16x16x32_bf16 v[44:47], v[162:165], v[212:215], v[44:47]
	v_mfma_f32_16x16x32_bf16 v[36:39], v[148:151], v[220:223], v[36:39]
	v_mfma_f32_16x16x32_bf16 v[28:31], v[162:165], v[220:223], v[28:31]
	v_mfma_f32_16x16x32_bf16 v[20:23], v[148:151], v[228:231], v[20:23]
	v_mfma_f32_16x16x32_bf16 v[12:15], v[162:165], v[228:231], v[12:15]
	v_mfma_f32_16x16x32_bf16 v[64:67], v[158:161], v[208:211], v[64:67]
	v_mfma_f32_16x16x32_bf16 v[60:63], v[166:169], v[208:211], v[60:63]
	v_mfma_f32_16x16x32_bf16 v[52:55], v[158:161], v[216:219], v[52:55]
	v_mfma_f32_16x16x32_bf16 v[44:47], v[166:169], v[216:219], v[44:47]
	v_mfma_f32_16x16x32_bf16 v[36:39], v[158:161], v[224:227], v[36:39]
	v_mfma_f32_16x16x32_bf16 v[28:31], v[166:169], v[224:227], v[28:31]
	v_mfma_f32_16x16x32_bf16 v[20:23], v[158:161], v[232:235], v[20:23]
	v_mfma_f32_16x16x32_bf16 v[12:15], v[166:169], v[232:235], v[12:15]
	s_setprio 0
	s_setprio 1
	v_mfma_f32_16x16x32_bf16 v[56:59], v[170:173], v[186:189], v[56:59]
	v_mfma_f32_16x16x32_bf16 v[48:51], v[178:181], v[186:189], v[48:51]
	v_mfma_f32_16x16x32_bf16 v[40:43], v[170:173], v[212:215], v[40:43]
	v_mfma_f32_16x16x32_bf16 v[32:35], v[178:181], v[212:215], v[32:35]
	v_mfma_f32_16x16x32_bf16 v[24:27], v[170:173], v[220:223], v[24:27]
	v_mfma_f32_16x16x32_bf16 v[16:19], v[178:181], v[220:223], v[16:19]
	v_mfma_f32_16x16x32_bf16 v[8:11], v[170:173], v[228:231], v[8:11]
	v_mfma_f32_16x16x32_bf16 v[4:7], v[178:181], v[228:231], v[4:7]
	v_mfma_f32_16x16x32_bf16 v[56:59], v[174:177], v[208:211], v[56:59]
	v_mfma_f32_16x16x32_bf16 v[48:51], v[182:185], v[208:211], v[48:51]
	v_mfma_f32_16x16x32_bf16 v[40:43], v[174:177], v[216:219], v[40:43]
	v_mfma_f32_16x16x32_bf16 v[32:35], v[182:185], v[216:219], v[32:35]
	v_mfma_f32_16x16x32_bf16 v[24:27], v[174:177], v[224:227], v[24:27]
	v_mfma_f32_16x16x32_bf16 v[16:19], v[182:185], v[224:227], v[16:19]
	v_mfma_f32_16x16x32_bf16 v[8:11], v[174:177], v[232:235], v[8:11]
	v_mfma_f32_16x16x32_bf16 v[4:7], v[182:185], v[232:235], v[4:7]
	s_setprio 0
	s_barrier
	s_add_i32 s51, s51, 2
	s_add_u32 s40, s40, 0x100
	s_addc_u32 s41, s41, 0
	s_add_u32 s42, s42, 0x100
	s_addc_u32 s43, s43, 0
	s_cmp_gt_u32 s51, 13
	s_cbranch_scc0 .LBB0_928
	s_lshl_b32 s5, s16, 8
	s_and_b64 vcc, exec, s[2:3]
	s_cbranch_vccz .LBB0_931
	v_or_b32_e32 v148, s5, v154
	v_ashrrev_i32_e32 v149, 31, v148
	v_lshlrev_b64 v[148:149], 6, v[148:149]
	v_lshl_add_u64 v[166:167], s[74:75], 0, v[148:149]
	global_load_dwordx4 v[148:151], v[166:167], off
	global_load_dwordx4 v[158:161], v[166:167], off offset:32
	global_load_dwordx4 v[162:165], v[166:167], off offset:16
	s_nop 0
	global_load_dwordx4 v[166:169], v[166:167], off offset:48
	s_barrier
